# final RMSNorm loop rewritten by hand: gain vector kept in registers, 4 rows per batch double-buffered with one counted vmcnt wait per batch (was 4+ serialized round trips per 2 rows)
# baseline (speedup 1.0000x reference)
; DI float bflo(unsigned w) { return __uint_as_float(w << 16); }
; DI float bfhi(unsigned w) { return __uint_as_float(w & 0xffff0000u); }
; __global__ void __launch_bounds__(512, 2) fwd_mega(Params p) {
;     ...
;   { int tidf = threadIdx.x; asm volatile("" : "+v"(tidf)); const int lane = tidf & 63; const int gw = bid * 8 + (tidf >> 6);
;     for (int m = gw; m < MTOK; m += 2 * NGW) {
;       const int m2 = (m + NGW < MTOK) ? m + NGW : m;
;       const float q1 = ssq[3 * MTOK + m], q2 = ssq[3 * MTOK + m2];
;       const u32x4* xr = (const u32x4*)(XB + (size_t)m * DM) + lane; const u32x4* xr2 = (const u32x4*)(XB + (size_t)m2 * DM) + lane;
;       const u32x4 va0 = xr[0], va1 = xr[64], vb0 = xr2[0], vb1 = xr2[64];
;       const f32x4* gr = (const f32x4*)p.final_norm;
; #pragma unroll
;       for (int rr = 0; rr < 2; ++rr) {
;         if (rr == 1 && m2 == m) break;
;         const float rstd = rsqrtf((rr ? q2 : q1) * (1.f / DM) + EPSN);
;         f32x4* orow = (f32x4*)(p.out + (size_t)(rr ? m2 : m) * DM);
; #pragma unroll
;         for (int j = 0; j < 2; ++j) { const u32x4 v = rr ? (j ? vb1 : vb0) : (j ? va1 : va0); const int c4 = (64 * j + lane) * 2;
;           const f32x4 g0 = gr[c4], g1 = gr[c4 + 1];
;           f32x4 o0, o1; o0[0] = bflo(v.x) * rstd * g0[0]; o0[1] = bfhi(v.x) * rstd * g0[1]; o0[2] = bflo(v.y) * rstd * g0[2]; o0[3] = bfhi(v.y) * rstd * g0[3];
;           o1[0] = bflo(v.z) * rstd * g1[0]; o1[1] = bfhi(v.z) * rstd * g1[1]; o1[2] = bflo(v.w) * rstd * g1[2]; o1[3] = bfhi(v.w) * rstd * g1[3];
;           __builtin_nontemporal_store(o0, &orow[c4]); __builtin_nontemporal_store(o1, &orow[c4 + 1]); }
;       }
;     } }
.LBB0_1410:
	s_or_b64 exec, exec, s[0:1]
	s_waitcnt lgkmcnt(0)
	s_barrier
	v_readlane_b32 s0, v252, 2
	v_ashrrev_i32_e32 v0, 6, v200
	s_mov_b32 s4, 0x10000
	v_add_u32_e32 v16, s0, v0
	v_cmp_gt_i32_e32 vcc, s4, v16
	s_and_saveexec_b64 s[0:1], vcc
	s_cbranch_execz .LBB0_1415
	v_readlane_b32 s6, v252, 0
	v_readlane_b32 s7, v252, 1
	v_readlane_b32 s48, v252, 11
	s_load_dwordx4 s[0:3], s[6:7], 0x98
	v_readfirstlane_b32 s8, v16
	v_and_b32_e32 v2, 63, v200
	v_lshlrev_b32_e32 v8, 4, v2
	v_lshlrev_b32_e32 v9, 5, v2
	v_mov_b32_e32 v18, 0x358637bd
	v_mov_b32_e32 v10, 0
	s_add_u32 s10, s56, 0xc0000
	s_addc_u32 s11, s57, 0
	s_mov_b32 s6, 0x800000
	s_waitcnt lgkmcnt(0)
	global_load_dwordx4 v[64:67], v9, s[0:1]
	global_load_dwordx4 v[68:71], v9, s[0:1] offset:16
	global_load_dwordx4 v[72:75], v9, s[0:1] offset:2048
	global_load_dwordx4 v[76:79], v9, s[0:1] offset:2064
	s_min_u32 s12, s8, 0xffff
	s_lshl_b32 s13, s12, 11
	s_add_u32 s14, s72, s13
	s_addc_u32 s15, s73, 0
	global_load_dwordx4 v[80:83], v8, s[14:15]
	global_load_dwordx4 v[84:87], v8, s[14:15] offset:1024
	s_lshl_b32 s13, s12, 2
	s_add_u32 s14, s10, s13
	s_addc_u32 s15, s11, 0
	global_load_dword v88, v10, s[14:15]
	s_mul_i32 s12, s48, 1
	s_add_u32 s12, s12, s8
	s_min_u32 s12, s12, 0xffff
	s_lshl_b32 s13, s12, 11
	s_add_u32 s14, s72, s13
	s_addc_u32 s15, s73, 0
	global_load_dwordx4 v[90:93], v8, s[14:15]
	global_load_dwordx4 v[94:97], v8, s[14:15] offset:1024
	s_lshl_b32 s13, s12, 2
	s_add_u32 s14, s10, s13
	s_addc_u32 s15, s11, 0
	global_load_dword v98, v10, s[14:15]
	s_mul_i32 s12, s48, 2
	s_add_u32 s12, s12, s8
	s_min_u32 s12, s12, 0xffff
	s_lshl_b32 s13, s12, 11
	s_add_u32 s14, s72, s13
	s_addc_u32 s15, s73, 0
	global_load_dwordx4 v[100:103], v8, s[14:15]
	global_load_dwordx4 v[104:107], v8, s[14:15] offset:1024
	s_lshl_b32 s13, s12, 2
	s_add_u32 s14, s10, s13
	s_addc_u32 s15, s11, 0
	global_load_dword v108, v10, s[14:15]
	s_mul_i32 s12, s48, 3
	s_add_u32 s12, s12, s8
	s_min_u32 s12, s12, 0xffff
	s_lshl_b32 s13, s12, 11
	s_add_u32 s14, s72, s13
	s_addc_u32 s15, s73, 0
	global_load_dwordx4 v[110:113], v8, s[14:15]
	global_load_dwordx4 v[114:117], v8, s[14:15] offset:1024
	s_lshl_b32 s13, s12, 2
	s_add_u32 s14, s10, s13
	s_addc_u32 s15, s11, 0
	global_load_dword v118, v10, s[14:15]
.Lfin_loop:
	s_lshl_b32 s18, s48, 2
	s_add_u32 s9, s8, s18
	s_min_u32 s12, s9, 0xffff
	s_lshl_b32 s13, s12, 11
	s_add_u32 s14, s72, s13
	s_addc_u32 s15, s73, 0
	global_load_dwordx4 v[120:123], v8, s[14:15]
	global_load_dwordx4 v[124:127], v8, s[14:15] offset:1024
	s_lshl_b32 s13, s12, 2
	s_add_u32 s14, s10, s13
	s_addc_u32 s15, s11, 0
	global_load_dword v128, v10, s[14:15]
	s_mul_i32 s12, s48, 1
	s_add_u32 s12, s12, s9
	s_min_u32 s12, s12, 0xffff
	s_lshl_b32 s13, s12, 11
	s_add_u32 s14, s72, s13
	s_addc_u32 s15, s73, 0
	global_load_dwordx4 v[130:133], v8, s[14:15]
	global_load_dwordx4 v[134:137], v8, s[14:15] offset:1024
	s_lshl_b32 s13, s12, 2
	s_add_u32 s14, s10, s13
	s_addc_u32 s15, s11, 0
	global_load_dword v138, v10, s[14:15]
	s_mul_i32 s12, s48, 2
	s_add_u32 s12, s12, s9
	s_min_u32 s12, s12, 0xffff
	s_lshl_b32 s13, s12, 11
	s_add_u32 s14, s72, s13
	s_addc_u32 s15, s73, 0
	global_load_dwordx4 v[140:143], v8, s[14:15]
	global_load_dwordx4 v[144:147], v8, s[14:15] offset:1024
	s_lshl_b32 s13, s12, 2
	s_add_u32 s14, s10, s13
	s_addc_u32 s15, s11, 0
	global_load_dword v148, v10, s[14:15]
	s_mul_i32 s12, s48, 3
	s_add_u32 s12, s12, s9
	s_min_u32 s12, s12, 0xffff
	s_lshl_b32 s13, s12, 11
	s_add_u32 s14, s72, s13
	s_addc_u32 s15, s73, 0
	global_load_dwordx4 v[150:153], v8, s[14:15]
	global_load_dwordx4 v[154:157], v8, s[14:15] offset:1024
	s_lshl_b32 s13, s12, 2
	s_add_u32 s14, s10, s13
	s_addc_u32 s15, s11, 0
	global_load_dword v158, v10, s[14:15]
	s_waitcnt vmcnt(12)
	s_mov_b32 s12, s8
	v_fmamk_f32 v20, v88, 0x3a800000, v18
	v_mul_f32_e32 v21, 0x4b800000, v20
	v_cmp_gt_f32_e32 vcc, s6, v20
	s_lshl_b32 s13, s12, 12
	s_add_u32 s16, s2, s13
	v_cndmask_b32_e32 v20, v20, v21, vcc
	v_rsq_f32_e32 v22, v20
	s_addc_u32 s17, s3, 0
	v_lshlrev_b32_e32 v24, 16, v80
	v_mul_f32_e32 v21, 0x45800000, v22
	v_and_b32_e32 v25, 0xffff0000, v80
	v_cndmask_b32_e32 v22, v22, v21, vcc
	v_lshlrev_b32_e32 v26, 16, v81
	v_and_b32_e32 v27, 0xffff0000, v81
	v_lshlrev_b32_e32 v28, 16, v82
	v_and_b32_e32 v29, 0xffff0000, v82
	v_lshlrev_b32_e32 v30, 16, v83
	v_and_b32_e32 v31, 0xffff0000, v83
	v_lshlrev_b32_e32 v32, 16, v84
	v_and_b32_e32 v33, 0xffff0000, v84
	v_lshlrev_b32_e32 v34, 16, v85
	v_and_b32_e32 v35, 0xffff0000, v85
	v_lshlrev_b32_e32 v36, 16, v86
	v_and_b32_e32 v37, 0xffff0000, v86
	v_lshlrev_b32_e32 v38, 16, v87
	v_and_b32_e32 v39, 0xffff0000, v87
	v_pk_mul_f32 v[24:25], v[22:23], v[24:25] op_sel_hi:[0,1]
	v_pk_mul_f32 v[26:27], v[22:23], v[26:27] op_sel_hi:[0,1]
	v_pk_mul_f32 v[28:29], v[22:23], v[28:29] op_sel_hi:[0,1]
	v_pk_mul_f32 v[30:31], v[22:23], v[30:31] op_sel_hi:[0,1]
	v_pk_mul_f32 v[32:33], v[22:23], v[32:33] op_sel_hi:[0,1]
	v_pk_mul_f32 v[34:35], v[22:23], v[34:35] op_sel_hi:[0,1]
	v_pk_mul_f32 v[36:37], v[22:23], v[36:37] op_sel_hi:[0,1]
	v_pk_mul_f32 v[38:39], v[22:23], v[38:39] op_sel_hi:[0,1]
	v_pk_mul_f32 v[24:25], v[64:65], v[24:25]
	v_pk_mul_f32 v[26:27], v[66:67], v[26:27]
	v_pk_mul_f32 v[28:29], v[68:69], v[28:29]
	v_pk_mul_f32 v[30:31], v[70:71], v[30:31]
	v_pk_mul_f32 v[32:33], v[72:73], v[32:33]
	v_pk_mul_f32 v[34:35], v[74:75], v[34:35]
	v_pk_mul_f32 v[36:37], v[76:77], v[36:37]
	v_pk_mul_f32 v[38:39], v[78:79], v[38:39]
	global_store_dwordx4 v9, v[24:27], s[16:17] nt
	global_store_dwordx4 v9, v[28:31], s[16:17] offset:16 nt
	global_store_dwordx4 v9, v[32:35], s[16:17] offset:2048 nt
	global_store_dwordx4 v9, v[36:39], s[16:17] offset:2064 nt
	s_mul_i32 s12, s48, 1
	s_add_u32 s12, s12, s8
	s_cmp_gt_u32 s12, 0xffff
	s_cbranch_scc1 .Lfin_skip_2
; DI float bflo(unsigned w) { return __uint_as_float(w << 16); }
; DI float bfhi(unsigned w) { return __uint_as_float(w & 0xffff0000u); }
; __global__ void __launch_bounds__(512, 2) fwd_mega(Params p) {
;     ...
;   { int tidf = threadIdx.x; asm volatile("" : "+v"(tidf)); const int lane = tidf & 63; const int gw = bid * 8 + (tidf >> 6);
;     for (int m = gw; m < MTOK; m += 2 * NGW) {
;       const int m2 = (m + NGW < MTOK) ? m + NGW : m;
;       const float q1 = ssq[3 * MTOK + m], q2 = ssq[3 * MTOK + m2];
;       const u32x4* xr = (const u32x4*)(XB + (size_t)m * DM) + lane; const u32x4* xr2 = (const u32x4*)(XB + (size_t)m2 * DM) + lane;
;       const u32x4 va0 = xr[0], va1 = xr[64], vb0 = xr2[0], vb1 = xr2[64];
;       const f32x4* gr = (const f32x4*)p.final_norm;
; #pragma unroll
;       for (int rr = 0; rr < 2; ++rr) {
;         if (rr == 1 && m2 == m) break;
;         const float rstd = rsqrtf((rr ? q2 : q1) * (1.f / DM) + EPSN);
;         f32x4* orow = (f32x4*)(p.out + (size_t)(rr ? m2 : m) * DM);
; #pragma unroll
;         for (int j = 0; j < 2; ++j) { const u32x4 v = rr ? (j ? vb1 : vb0) : (j ? va1 : va0); const int c4 = (64 * j + lane) * 2;
;           const f32x4 g0 = gr[c4], g1 = gr[c4 + 1];
;           f32x4 o0, o1; o0[0] = bflo(v.x) * rstd * g0[0]; o0[1] = bfhi(v.x) * rstd * g0[1]; o0[2] = bflo(v.y) * rstd * g0[2]; o0[3] = bfhi(v.y) * rstd * g0[3];
;           o1[0] = bflo(v.z) * rstd * g1[0]; o1[1] = bfhi(v.z) * rstd * g1[1]; o1[2] = bflo(v.w) * rstd * g1[2]; o1[3] = bfhi(v.w) * rstd * g1[3];
;           __builtin_nontemporal_store(o0, &orow[c4]); __builtin_nontemporal_store(o1, &orow[c4 + 1]); }
;       }
;     } }
	v_fmamk_f32 v20, v98, 0x3a800000, v18
	v_mul_f32_e32 v21, 0x4b800000, v20
	v_cmp_gt_f32_e32 vcc, s6, v20
	s_lshl_b32 s13, s12, 12
	s_add_u32 s16, s2, s13
	v_cndmask_b32_e32 v20, v20, v21, vcc
	v_rsq_f32_e32 v22, v20
	s_addc_u32 s17, s3, 0
	v_lshlrev_b32_e32 v24, 16, v90
	v_mul_f32_e32 v21, 0x45800000, v22
	v_and_b32_e32 v25, 0xffff0000, v90
	v_cndmask_b32_e32 v22, v22, v21, vcc
	v_lshlrev_b32_e32 v26, 16, v91
	v_and_b32_e32 v27, 0xffff0000, v91
	v_lshlrev_b32_e32 v28, 16, v92
	v_and_b32_e32 v29, 0xffff0000, v92
	v_lshlrev_b32_e32 v30, 16, v93
	v_and_b32_e32 v31, 0xffff0000, v93
	v_lshlrev_b32_e32 v32, 16, v94
	v_and_b32_e32 v33, 0xffff0000, v94
	v_lshlrev_b32_e32 v34, 16, v95
	v_and_b32_e32 v35, 0xffff0000, v95
	v_lshlrev_b32_e32 v36, 16, v96
	v_and_b32_e32 v37, 0xffff0000, v96
	v_lshlrev_b32_e32 v38, 16, v97
	v_and_b32_e32 v39, 0xffff0000, v97
	v_pk_mul_f32 v[24:25], v[22:23], v[24:25] op_sel_hi:[0,1]
	v_pk_mul_f32 v[26:27], v[22:23], v[26:27] op_sel_hi:[0,1]
	v_pk_mul_f32 v[28:29], v[22:23], v[28:29] op_sel_hi:[0,1]
	v_pk_mul_f32 v[30:31], v[22:23], v[30:31] op_sel_hi:[0,1]
	v_pk_mul_f32 v[32:33], v[22:23], v[32:33] op_sel_hi:[0,1]
	v_pk_mul_f32 v[34:35], v[22:23], v[34:35] op_sel_hi:[0,1]
	v_pk_mul_f32 v[36:37], v[22:23], v[36:37] op_sel_hi:[0,1]
	v_pk_mul_f32 v[38:39], v[22:23], v[38:39] op_sel_hi:[0,1]
	v_pk_mul_f32 v[24:25], v[64:65], v[24:25]
	v_pk_mul_f32 v[26:27], v[66:67], v[26:27]
	v_pk_mul_f32 v[28:29], v[68:69], v[28:29]
	v_pk_mul_f32 v[30:31], v[70:71], v[30:31]
	v_pk_mul_f32 v[32:33], v[72:73], v[32:33]
	v_pk_mul_f32 v[34:35], v[74:75], v[34:35]
	v_pk_mul_f32 v[36:37], v[76:77], v[36:37]
	v_pk_mul_f32 v[38:39], v[78:79], v[38:39]
	global_store_dwordx4 v9, v[24:27], s[16:17] nt
	global_store_dwordx4 v9, v[28:31], s[16:17] offset:16 nt
	global_store_dwordx4 v9, v[32:35], s[16:17] offset:2048 nt
	global_store_dwordx4 v9, v[36:39], s[16:17] offset:2064 nt
.Lfin_skip_2:
	s_mul_i32 s12, s48, 2
	s_add_u32 s12, s12, s8
	s_cmp_gt_u32 s12, 0xffff
	s_cbranch_scc1 .Lfin_skip_3
	v_fmamk_f32 v20, v108, 0x3a800000, v18
	v_mul_f32_e32 v21, 0x4b800000, v20
	v_cmp_gt_f32_e32 vcc, s6, v20
	s_lshl_b32 s13, s12, 12
	s_add_u32 s16, s2, s13
	v_cndmask_b32_e32 v20, v20, v21, vcc
	v_rsq_f32_e32 v22, v20
	s_addc_u32 s17, s3, 0
	v_lshlrev_b32_e32 v24, 16, v100
	v_mul_f32_e32 v21, 0x45800000, v22
	v_and_b32_e32 v25, 0xffff0000, v100
	v_cndmask_b32_e32 v22, v22, v21, vcc
	v_lshlrev_b32_e32 v26, 16, v101
	v_and_b32_e32 v27, 0xffff0000, v101
	v_lshlrev_b32_e32 v28, 16, v102
	v_and_b32_e32 v29, 0xffff0000, v102
	v_lshlrev_b32_e32 v30, 16, v103
	v_and_b32_e32 v31, 0xffff0000, v103
	v_lshlrev_b32_e32 v32, 16, v104
	v_and_b32_e32 v33, 0xffff0000, v104
	v_lshlrev_b32_e32 v34, 16, v105
	v_and_b32_e32 v35, 0xffff0000, v105
	v_lshlrev_b32_e32 v36, 16, v106
	v_and_b32_e32 v37, 0xffff0000, v106
	v_lshlrev_b32_e32 v38, 16, v107
	v_and_b32_e32 v39, 0xffff0000, v107
	v_pk_mul_f32 v[24:25], v[22:23], v[24:25] op_sel_hi:[0,1]
	v_pk_mul_f32 v[26:27], v[22:23], v[26:27] op_sel_hi:[0,1]
	v_pk_mul_f32 v[28:29], v[22:23], v[28:29] op_sel_hi:[0,1]
	v_pk_mul_f32 v[30:31], v[22:23], v[30:31] op_sel_hi:[0,1]
	v_pk_mul_f32 v[32:33], v[22:23], v[32:33] op_sel_hi:[0,1]
	v_pk_mul_f32 v[34:35], v[22:23], v[34:35] op_sel_hi:[0,1]
	v_pk_mul_f32 v[36:37], v[22:23], v[36:37] op_sel_hi:[0,1]
	v_pk_mul_f32 v[38:39], v[22:23], v[38:39] op_sel_hi:[0,1]
	v_pk_mul_f32 v[24:25], v[64:65], v[24:25]
	v_pk_mul_f32 v[26:27], v[66:67], v[26:27]
	v_pk_mul_f32 v[28:29], v[68:69], v[28:29]
	v_pk_mul_f32 v[30:31], v[70:71], v[30:31]
	v_pk_mul_f32 v[32:33], v[72:73], v[32:33]
	v_pk_mul_f32 v[34:35], v[74:75], v[34:35]
	v_pk_mul_f32 v[36:37], v[76:77], v[36:37]
	v_pk_mul_f32 v[38:39], v[78:79], v[38:39]
	global_store_dwordx4 v9, v[24:27], s[16:17] nt
	global_store_dwordx4 v9, v[28:31], s[16:17] offset:16 nt
	global_store_dwordx4 v9, v[32:35], s[16:17] offset:2048 nt
	global_store_dwordx4 v9, v[36:39], s[16:17] offset:2064 nt
.Lfin_skip_3:
	s_mul_i32 s12, s48, 3
	s_add_u32 s12, s12, s8
	s_cmp_gt_u32 s12, 0xffff
	s_cbranch_scc1 .Lfin_skip_4
	v_fmamk_f32 v20, v118, 0x3a800000, v18
	v_mul_f32_e32 v21, 0x4b800000, v20
	v_cmp_gt_f32_e32 vcc, s6, v20
	s_lshl_b32 s13, s12, 12
	s_add_u32 s16, s2, s13
	v_cndmask_b32_e32 v20, v20, v21, vcc
	v_rsq_f32_e32 v22, v20
	s_addc_u32 s17, s3, 0
	v_lshlrev_b32_e32 v24, 16, v110
	v_mul_f32_e32 v21, 0x45800000, v22
	v_and_b32_e32 v25, 0xffff0000, v110
	v_cndmask_b32_e32 v22, v22, v21, vcc
	v_lshlrev_b32_e32 v26, 16, v111
	v_and_b32_e32 v27, 0xffff0000, v111
	v_lshlrev_b32_e32 v28, 16, v112
	v_and_b32_e32 v29, 0xffff0000, v112
	v_lshlrev_b32_e32 v30, 16, v113
	v_and_b32_e32 v31, 0xffff0000, v113
	v_lshlrev_b32_e32 v32, 16, v114
	v_and_b32_e32 v33, 0xffff0000, v114
	v_lshlrev_b32_e32 v34, 16, v115
	v_and_b32_e32 v35, 0xffff0000, v115
	v_lshlrev_b32_e32 v36, 16, v116
	v_and_b32_e32 v37, 0xffff0000, v116
	v_lshlrev_b32_e32 v38, 16, v117
	v_and_b32_e32 v39, 0xffff0000, v117
	v_pk_mul_f32 v[24:25], v[22:23], v[24:25] op_sel_hi:[0,1]
	v_pk_mul_f32 v[26:27], v[22:23], v[26:27] op_sel_hi:[0,1]
	v_pk_mul_f32 v[28:29], v[22:23], v[28:29] op_sel_hi:[0,1]
	v_pk_mul_f32 v[30:31], v[22:23], v[30:31] op_sel_hi:[0,1]
	v_pk_mul_f32 v[32:33], v[22:23], v[32:33] op_sel_hi:[0,1]
	v_pk_mul_f32 v[34:35], v[22:23], v[34:35] op_sel_hi:[0,1]
	v_pk_mul_f32 v[36:37], v[22:23], v[36:37] op_sel_hi:[0,1]
	v_pk_mul_f32 v[38:39], v[22:23], v[38:39] op_sel_hi:[0,1]
	v_pk_mul_f32 v[24:25], v[64:65], v[24:25]
	v_pk_mul_f32 v[26:27], v[66:67], v[26:27]
	v_pk_mul_f32 v[28:29], v[68:69], v[28:29]
	v_pk_mul_f32 v[30:31], v[70:71], v[30:31]
	v_pk_mul_f32 v[32:33], v[72:73], v[32:33]
	v_pk_mul_f32 v[34:35], v[74:75], v[34:35]
	v_pk_mul_f32 v[36:37], v[76:77], v[36:37]
	v_pk_mul_f32 v[38:39], v[78:79], v[38:39]
	global_store_dwordx4 v9, v[24:27], s[16:17] nt
	global_store_dwordx4 v9, v[28:31], s[16:17] offset:16 nt
	global_store_dwordx4 v9, v[32:35], s[16:17] offset:2048 nt
	global_store_dwordx4 v9, v[36:39], s[16:17] offset:2064 nt
; DI float bflo(unsigned w) { return __uint_as_float(w << 16); }
; DI float bfhi(unsigned w) { return __uint_as_float(w & 0xffff0000u); }
; __global__ void __launch_bounds__(512, 2) fwd_mega(Params p) {
;     ...
;   { int tidf = threadIdx.x; asm volatile("" : "+v"(tidf)); const int lane = tidf & 63; const int gw = bid * 8 + (tidf >> 6);
;     for (int m = gw; m < MTOK; m += 2 * NGW) {
;       const int m2 = (m + NGW < MTOK) ? m + NGW : m;
;       const float q1 = ssq[3 * MTOK + m], q2 = ssq[3 * MTOK + m2];
;       const u32x4* xr = (const u32x4*)(XB + (size_t)m * DM) + lane; const u32x4* xr2 = (const u32x4*)(XB + (size_t)m2 * DM) + lane;
;       const u32x4 va0 = xr[0], va1 = xr[64], vb0 = xr2[0], vb1 = xr2[64];
;       const f32x4* gr = (const f32x4*)p.final_norm;
; #pragma unroll
;       for (int rr = 0; rr < 2; ++rr) {
;         if (rr == 1 && m2 == m) break;
;         const float rstd = rsqrtf((rr ? q2 : q1) * (1.f / DM) + EPSN);
;         f32x4* orow = (f32x4*)(p.out + (size_t)(rr ? m2 : m) * DM);
; #pragma unroll
;         for (int j = 0; j < 2; ++j) { const u32x4 v = rr ? (j ? vb1 : vb0) : (j ? va1 : va0); const int c4 = (64 * j + lane) * 2;
;           const f32x4 g0 = gr[c4], g1 = gr[c4 + 1];
;           f32x4 o0, o1; o0[0] = bflo(v.x) * rstd * g0[0]; o0[1] = bfhi(v.x) * rstd * g0[1]; o0[2] = bflo(v.y) * rstd * g0[2]; o0[3] = bfhi(v.y) * rstd * g0[3];
;           o1[0] = bflo(v.z) * rstd * g1[0]; o1[1] = bfhi(v.z) * rstd * g1[1]; o1[2] = bflo(v.w) * rstd * g1[2]; o1[3] = bfhi(v.w) * rstd * g1[3];
;           __builtin_nontemporal_store(o0, &orow[c4]); __builtin_nontemporal_store(o1, &orow[c4 + 1]); }
;       }
;     } }
.Lfin_skip_4:
	s_cmp_gt_u32 s9, 0xffff
	s_cbranch_scc1 .LBB0_1415
	s_add_u32 s8, s9, s18
	s_min_u32 s12, s8, 0xffff
	s_lshl_b32 s13, s12, 11
	s_add_u32 s14, s72, s13
	s_addc_u32 s15, s73, 0
	global_load_dwordx4 v[80:83], v8, s[14:15]
	global_load_dwordx4 v[84:87], v8, s[14:15] offset:1024
	s_lshl_b32 s13, s12, 2
	s_add_u32 s14, s10, s13
	s_addc_u32 s15, s11, 0
	global_load_dword v88, v10, s[14:15]
	s_mul_i32 s12, s48, 1
	s_add_u32 s12, s12, s8
	s_min_u32 s12, s12, 0xffff
	s_lshl_b32 s13, s12, 11
	s_add_u32 s14, s72, s13
	s_addc_u32 s15, s73, 0
	global_load_dwordx4 v[90:93], v8, s[14:15]
	global_load_dwordx4 v[94:97], v8, s[14:15] offset:1024
	s_lshl_b32 s13, s12, 2
	s_add_u32 s14, s10, s13
	s_addc_u32 s15, s11, 0
	global_load_dword v98, v10, s[14:15]
	s_mul_i32 s12, s48, 2
	s_add_u32 s12, s12, s8
	s_min_u32 s12, s12, 0xffff
	s_lshl_b32 s13, s12, 11
	s_add_u32 s14, s72, s13
	s_addc_u32 s15, s73, 0
	global_load_dwordx4 v[100:103], v8, s[14:15]
	global_load_dwordx4 v[104:107], v8, s[14:15] offset:1024
	s_lshl_b32 s13, s12, 2
	s_add_u32 s14, s10, s13
	s_addc_u32 s15, s11, 0
	global_load_dword v108, v10, s[14:15]
	s_mul_i32 s12, s48, 3
	s_add_u32 s12, s12, s8
	s_min_u32 s12, s12, 0xffff
	s_lshl_b32 s13, s12, 11
	s_add_u32 s14, s72, s13
	s_addc_u32 s15, s73, 0
	global_load_dwordx4 v[110:113], v8, s[14:15]
	global_load_dwordx4 v[114:117], v8, s[14:15] offset:1024
	s_lshl_b32 s13, s12, 2
	s_add_u32 s14, s10, s13
	s_addc_u32 s15, s11, 0
	global_load_dword v118, v10, s[14:15]
	s_waitcnt vmcnt(12)
	s_mov_b32 s12, s9
	v_fmamk_f32 v20, v128, 0x3a800000, v18
	v_mul_f32_e32 v21, 0x4b800000, v20
	v_cmp_gt_f32_e32 vcc, s6, v20
	s_lshl_b32 s13, s12, 12
	s_add_u32 s16, s2, s13
	v_cndmask_b32_e32 v20, v20, v21, vcc
	v_rsq_f32_e32 v22, v20
	s_addc_u32 s17, s3, 0
	v_lshlrev_b32_e32 v24, 16, v120
	v_mul_f32_e32 v21, 0x45800000, v22
	v_and_b32_e32 v25, 0xffff0000, v120
	v_cndmask_b32_e32 v22, v22, v21, vcc
	v_lshlrev_b32_e32 v26, 16, v121
	v_and_b32_e32 v27, 0xffff0000, v121
	v_lshlrev_b32_e32 v28, 16, v122
	v_and_b32_e32 v29, 0xffff0000, v122
	v_lshlrev_b32_e32 v30, 16, v123
	v_and_b32_e32 v31, 0xffff0000, v123
	v_lshlrev_b32_e32 v32, 16, v124
	v_and_b32_e32 v33, 0xffff0000, v124
	v_lshlrev_b32_e32 v34, 16, v125
	v_and_b32_e32 v35, 0xffff0000, v125
	v_lshlrev_b32_e32 v36, 16, v126
	v_and_b32_e32 v37, 0xffff0000, v126
	v_lshlrev_b32_e32 v38, 16, v127
	v_and_b32_e32 v39, 0xffff0000, v127
	v_pk_mul_f32 v[24:25], v[22:23], v[24:25] op_sel_hi:[0,1]
	v_pk_mul_f32 v[26:27], v[22:23], v[26:27] op_sel_hi:[0,1]
	v_pk_mul_f32 v[28:29], v[22:23], v[28:29] op_sel_hi:[0,1]
	v_pk_mul_f32 v[30:31], v[22:23], v[30:31] op_sel_hi:[0,1]
	v_pk_mul_f32 v[32:33], v[22:23], v[32:33] op_sel_hi:[0,1]
	v_pk_mul_f32 v[34:35], v[22:23], v[34:35] op_sel_hi:[0,1]
	v_pk_mul_f32 v[36:37], v[22:23], v[36:37] op_sel_hi:[0,1]
	v_pk_mul_f32 v[38:39], v[22:23], v[38:39] op_sel_hi:[0,1]
	v_pk_mul_f32 v[24:25], v[64:65], v[24:25]
	v_pk_mul_f32 v[26:27], v[66:67], v[26:27]
	v_pk_mul_f32 v[28:29], v[68:69], v[28:29]
	v_pk_mul_f32 v[30:31], v[70:71], v[30:31]
	v_pk_mul_f32 v[32:33], v[72:73], v[32:33]
	v_pk_mul_f32 v[34:35], v[74:75], v[34:35]
	v_pk_mul_f32 v[36:37], v[76:77], v[36:37]
	v_pk_mul_f32 v[38:39], v[78:79], v[38:39]
	global_store_dwordx4 v9, v[24:27], s[16:17] nt
	global_store_dwordx4 v9, v[28:31], s[16:17] offset:16 nt
	global_store_dwordx4 v9, v[32:35], s[16:17] offset:2048 nt
	global_store_dwordx4 v9, v[36:39], s[16:17] offset:2064 nt
	s_mul_i32 s12, s48, 1
	s_add_u32 s12, s12, s9
	s_cmp_gt_u32 s12, 0xffff
	s_cbranch_scc1 .Lfin_skip_6
	v_fmamk_f32 v20, v138, 0x3a800000, v18
	v_mul_f32_e32 v21, 0x4b800000, v20
	v_cmp_gt_f32_e32 vcc, s6, v20
	s_lshl_b32 s13, s12, 12
	s_add_u32 s16, s2, s13
	v_cndmask_b32_e32 v20, v20, v21, vcc
	v_rsq_f32_e32 v22, v20
	s_addc_u32 s17, s3, 0
	v_lshlrev_b32_e32 v24, 16, v130
	v_mul_f32_e32 v21, 0x45800000, v22
	v_and_b32_e32 v25, 0xffff0000, v130
	v_cndmask_b32_e32 v22, v22, v21, vcc
	v_lshlrev_b32_e32 v26, 16, v131
	v_and_b32_e32 v27, 0xffff0000, v131
	v_lshlrev_b32_e32 v28, 16, v132
	v_and_b32_e32 v29, 0xffff0000, v132
	v_lshlrev_b32_e32 v30, 16, v133
	v_and_b32_e32 v31, 0xffff0000, v133
	v_lshlrev_b32_e32 v32, 16, v134
	v_and_b32_e32 v33, 0xffff0000, v134
	v_lshlrev_b32_e32 v34, 16, v135
	v_and_b32_e32 v35, 0xffff0000, v135
	v_lshlrev_b32_e32 v36, 16, v136
	v_and_b32_e32 v37, 0xffff0000, v136
	v_lshlrev_b32_e32 v38, 16, v137
	v_and_b32_e32 v39, 0xffff0000, v137
	v_pk_mul_f32 v[24:25], v[22:23], v[24:25] op_sel_hi:[0,1]
	v_pk_mul_f32 v[26:27], v[22:23], v[26:27] op_sel_hi:[0,1]
	v_pk_mul_f32 v[28:29], v[22:23], v[28:29] op_sel_hi:[0,1]
	v_pk_mul_f32 v[30:31], v[22:23], v[30:31] op_sel_hi:[0,1]
	v_pk_mul_f32 v[32:33], v[22:23], v[32:33] op_sel_hi:[0,1]
	v_pk_mul_f32 v[34:35], v[22:23], v[34:35] op_sel_hi:[0,1]
	v_pk_mul_f32 v[36:37], v[22:23], v[36:37] op_sel_hi:[0,1]
	v_pk_mul_f32 v[38:39], v[22:23], v[38:39] op_sel_hi:[0,1]
	v_pk_mul_f32 v[24:25], v[64:65], v[24:25]
	v_pk_mul_f32 v[26:27], v[66:67], v[26:27]
	v_pk_mul_f32 v[28:29], v[68:69], v[28:29]
	v_pk_mul_f32 v[30:31], v[70:71], v[30:31]
	v_pk_mul_f32 v[32:33], v[72:73], v[32:33]
	v_pk_mul_f32 v[34:35], v[74:75], v[34:35]
	v_pk_mul_f32 v[36:37], v[76:77], v[36:37]
	v_pk_mul_f32 v[38:39], v[78:79], v[38:39]
	global_store_dwordx4 v9, v[24:27], s[16:17] nt
	global_store_dwordx4 v9, v[28:31], s[16:17] offset:16 nt
	global_store_dwordx4 v9, v[32:35], s[16:17] offset:2048 nt
	global_store_dwordx4 v9, v[36:39], s[16:17] offset:2064 nt
; DI float bflo(unsigned w) { return __uint_as_float(w << 16); }
; DI float bfhi(unsigned w) { return __uint_as_float(w & 0xffff0000u); }
; __global__ void __launch_bounds__(512, 2) fwd_mega(Params p) {
;     ...
;   { int tidf = threadIdx.x; asm volatile("" : "+v"(tidf)); const int lane = tidf & 63; const int gw = bid * 8 + (tidf >> 6);
;     for (int m = gw; m < MTOK; m += 2 * NGW) {
;       const int m2 = (m + NGW < MTOK) ? m + NGW : m;
;       const float q1 = ssq[3 * MTOK + m], q2 = ssq[3 * MTOK + m2];
;       const u32x4* xr = (const u32x4*)(XB + (size_t)m * DM) + lane; const u32x4* xr2 = (const u32x4*)(XB + (size_t)m2 * DM) + lane;
;       const u32x4 va0 = xr[0], va1 = xr[64], vb0 = xr2[0], vb1 = xr2[64];
;       const f32x4* gr = (const f32x4*)p.final_norm;
; #pragma unroll
;       for (int rr = 0; rr < 2; ++rr) {
;         if (rr == 1 && m2 == m) break;
;         const float rstd = rsqrtf((rr ? q2 : q1) * (1.f / DM) + EPSN);
;         f32x4* orow = (f32x4*)(p.out + (size_t)(rr ? m2 : m) * DM);
; #pragma unroll
;         for (int j = 0; j < 2; ++j) { const u32x4 v = rr ? (j ? vb1 : vb0) : (j ? va1 : va0); const int c4 = (64 * j + lane) * 2;
;           const f32x4 g0 = gr[c4], g1 = gr[c4 + 1];
;           f32x4 o0, o1; o0[0] = bflo(v.x) * rstd * g0[0]; o0[1] = bfhi(v.x) * rstd * g0[1]; o0[2] = bflo(v.y) * rstd * g0[2]; o0[3] = bfhi(v.y) * rstd * g0[3];
;           o1[0] = bflo(v.z) * rstd * g1[0]; o1[1] = bfhi(v.z) * rstd * g1[1]; o1[2] = bflo(v.w) * rstd * g1[2]; o1[3] = bfhi(v.w) * rstd * g1[3];
;           __builtin_nontemporal_store(o0, &orow[c4]); __builtin_nontemporal_store(o1, &orow[c4 + 1]); }
;       }
;     } }
.Lfin_skip_6:
	s_mul_i32 s12, s48, 2
	s_add_u32 s12, s12, s9
	s_cmp_gt_u32 s12, 0xffff
	s_cbranch_scc1 .Lfin_skip_7
	v_fmamk_f32 v20, v148, 0x3a800000, v18
	v_mul_f32_e32 v21, 0x4b800000, v20
	v_cmp_gt_f32_e32 vcc, s6, v20
	s_lshl_b32 s13, s12, 12
	s_add_u32 s16, s2, s13
	v_cndmask_b32_e32 v20, v20, v21, vcc
	v_rsq_f32_e32 v22, v20
	s_addc_u32 s17, s3, 0
	v_lshlrev_b32_e32 v24, 16, v140
	v_mul_f32_e32 v21, 0x45800000, v22
	v_and_b32_e32 v25, 0xffff0000, v140
	v_cndmask_b32_e32 v22, v22, v21, vcc
	v_lshlrev_b32_e32 v26, 16, v141
	v_and_b32_e32 v27, 0xffff0000, v141
	v_lshlrev_b32_e32 v28, 16, v142
	v_and_b32_e32 v29, 0xffff0000, v142
	v_lshlrev_b32_e32 v30, 16, v143
	v_and_b32_e32 v31, 0xffff0000, v143
	v_lshlrev_b32_e32 v32, 16, v144
	v_and_b32_e32 v33, 0xffff0000, v144
	v_lshlrev_b32_e32 v34, 16, v145
	v_and_b32_e32 v35, 0xffff0000, v145
	v_lshlrev_b32_e32 v36, 16, v146
	v_and_b32_e32 v37, 0xffff0000, v146
	v_lshlrev_b32_e32 v38, 16, v147
	v_and_b32_e32 v39, 0xffff0000, v147
	v_pk_mul_f32 v[24:25], v[22:23], v[24:25] op_sel_hi:[0,1]
	v_pk_mul_f32 v[26:27], v[22:23], v[26:27] op_sel_hi:[0,1]
	v_pk_mul_f32 v[28:29], v[22:23], v[28:29] op_sel_hi:[0,1]
	v_pk_mul_f32 v[30:31], v[22:23], v[30:31] op_sel_hi:[0,1]
	v_pk_mul_f32 v[32:33], v[22:23], v[32:33] op_sel_hi:[0,1]
	v_pk_mul_f32 v[34:35], v[22:23], v[34:35] op_sel_hi:[0,1]
	v_pk_mul_f32 v[36:37], v[22:23], v[36:37] op_sel_hi:[0,1]
	v_pk_mul_f32 v[38:39], v[22:23], v[38:39] op_sel_hi:[0,1]
	v_pk_mul_f32 v[24:25], v[64:65], v[24:25]
	v_pk_mul_f32 v[26:27], v[66:67], v[26:27]
	v_pk_mul_f32 v[28:29], v[68:69], v[28:29]
	v_pk_mul_f32 v[30:31], v[70:71], v[30:31]
	v_pk_mul_f32 v[32:33], v[72:73], v[32:33]
	v_pk_mul_f32 v[34:35], v[74:75], v[34:35]
	v_pk_mul_f32 v[36:37], v[76:77], v[36:37]
	v_pk_mul_f32 v[38:39], v[78:79], v[38:39]
	global_store_dwordx4 v9, v[24:27], s[16:17] nt
	global_store_dwordx4 v9, v[28:31], s[16:17] offset:16 nt
	global_store_dwordx4 v9, v[32:35], s[16:17] offset:2048 nt
	global_store_dwordx4 v9, v[36:39], s[16:17] offset:2064 nt
.Lfin_skip_7:
	s_mul_i32 s12, s48, 3
	s_add_u32 s12, s12, s9
	s_cmp_gt_u32 s12, 0xffff
	s_cbranch_scc1 .Lfin_skip_8
	v_fmamk_f32 v20, v158, 0x3a800000, v18
	v_mul_f32_e32 v21, 0x4b800000, v20
	v_cmp_gt_f32_e32 vcc, s6, v20
	s_lshl_b32 s13, s12, 12
	s_add_u32 s16, s2, s13
	v_cndmask_b32_e32 v20, v20, v21, vcc
	v_rsq_f32_e32 v22, v20
	s_addc_u32 s17, s3, 0
	v_lshlrev_b32_e32 v24, 16, v150
	v_mul_f32_e32 v21, 0x45800000, v22
	v_and_b32_e32 v25, 0xffff0000, v150
	v_cndmask_b32_e32 v22, v22, v21, vcc
	v_lshlrev_b32_e32 v26, 16, v151
	v_and_b32_e32 v27, 0xffff0000, v151
	v_lshlrev_b32_e32 v28, 16, v152
	v_and_b32_e32 v29, 0xffff0000, v152
	v_lshlrev_b32_e32 v30, 16, v153
	v_and_b32_e32 v31, 0xffff0000, v153
	v_lshlrev_b32_e32 v32, 16, v154
	v_and_b32_e32 v33, 0xffff0000, v154
	v_lshlrev_b32_e32 v34, 16, v155
	v_and_b32_e32 v35, 0xffff0000, v155
	v_lshlrev_b32_e32 v36, 16, v156
	v_and_b32_e32 v37, 0xffff0000, v156
	v_lshlrev_b32_e32 v38, 16, v157
	v_and_b32_e32 v39, 0xffff0000, v157
	v_pk_mul_f32 v[24:25], v[22:23], v[24:25] op_sel_hi:[0,1]
	v_pk_mul_f32 v[26:27], v[22:23], v[26:27] op_sel_hi:[0,1]
	v_pk_mul_f32 v[28:29], v[22:23], v[28:29] op_sel_hi:[0,1]
	v_pk_mul_f32 v[30:31], v[22:23], v[30:31] op_sel_hi:[0,1]
	v_pk_mul_f32 v[32:33], v[22:23], v[32:33] op_sel_hi:[0,1]
	v_pk_mul_f32 v[34:35], v[22:23], v[34:35] op_sel_hi:[0,1]
	v_pk_mul_f32 v[36:37], v[22:23], v[36:37] op_sel_hi:[0,1]
	v_pk_mul_f32 v[38:39], v[22:23], v[38:39] op_sel_hi:[0,1]
	v_pk_mul_f32 v[24:25], v[64:65], v[24:25]
	v_pk_mul_f32 v[26:27], v[66:67], v[26:27]
	v_pk_mul_f32 v[28:29], v[68:69], v[28:29]
	v_pk_mul_f32 v[30:31], v[70:71], v[30:31]
	v_pk_mul_f32 v[32:33], v[72:73], v[32:33]
	v_pk_mul_f32 v[34:35], v[74:75], v[34:35]
	v_pk_mul_f32 v[36:37], v[76:77], v[36:37]
	v_pk_mul_f32 v[38:39], v[78:79], v[38:39]
	global_store_dwordx4 v9, v[24:27], s[16:17] nt
	global_store_dwordx4 v9, v[28:31], s[16:17] offset:16 nt
	global_store_dwordx4 v9, v[32:35], s[16:17] offset:2048 nt
	global_store_dwordx4 v9, v[36:39], s[16:17] offset:2064 nt
.Lfin_skip_8:
	s_cmp_gt_u32 s8, 0xffff
	s_cbranch_scc0 .Lfin_loop
